# PH8 GEMM loop: LDS-DMA uses SGPR-base + 32-bit VGPR offset addressing, removing 26 v_lshl_add_u64 per K iteration from the load segments
# speedup vs baseline: 1.0076x; 1.0068x over previous
; #define PG8_STAGE(bufoff, gbase, RR, ld) do { _Pragma("unroll") for (int _i = 0; _i < 2; ++_i) \
;         __builtin_amdgcn_global_load_lds((const unsigned*)((const char*)(gbase) + (RR)[_i] * (ld) + C2[_i]), (LAS unsigned*)(lds + (bufoff) + ldsw + _i * 8192), 16, 0, 0); } while (0)
; #define PG8_WAIT_V(n) asm volatile("s_waitcnt vmcnt(" #n ")" ::: "memory")
; #define PG8_BAR __builtin_amdgcn_s_barrier()
; template <class Sched, class Epi>
; __device__ __forceinline__ void gemm_run(LAS unsigned char* lds, const Sched& S, const Epi& E) {
;     ...
;     for (int i = 0; i < 2; ++i) { int R, C; stage_rc(tid * 16 + i * 8192, R, C); RA[i] = (unsigned)R; RB[i] = (unsigned)((R & ~31) + perm32(R & 31)); C2[i] = (unsigned)(C * 2); }
;     const unsigned ldsw = (unsigned)wid * 1024u;
;     const int aoff = lds_byte(wr * 64 + fr, fq * 8), boff = lds_byte(wc * 32 + fr, fq * 8);
;     ...
;     PG8_STAGE(PG8_SB(0, 0), cB, RB, ldb); PG8_STAGE(PG8_SB(0, 1), cB + (size_t)HALF * ldb, RB, ldb); PG8_STAGE(PG8_SA(0, 0), cA, RA, lda); PG8_STAGE(PG8_SA(0, 1), cA + (size_t)HALF * lda, RA, lda);
;     if (wr == 1) PG8_BAR;
;     PG8_WAIT_V(2); PG8_BAR;
;     PG8_STAGE(PG8_SB(1, 0), cB + kstep, RB, ldb); PG8_STAGE(PG8_SA(1, 0), cA + kstep, RA, lda); PG8_STAGE(PG8_SB(1, 1), cB + (size_t)HALF * ldb + kstep, RB, ldb);
;     PG8_WAIT_V(6); PG8_BAR;
.LBB0_993:
	s_lshl_b32 s6, s6, 5
	s_and_b32 s16, s6, 0x60
	s_mov_b64 s[6:7], 0x80
	s_add_i32 m0, s42, 0x18000
	v_lshl_add_u64 v[2:3], v[2:3], 0, s[6:7]
	s_lshl_b32 s11, s10, 13
	s_lshl_b32 s14, s16, 7
	s_waitcnt vmcnt(2)
	s_barrier
	global_load_lds_dwordx4 v[2:3], off
	v_lshl_add_u64 v[2:3], v[4:5], 0, s[6:7]
	s_add_i32 m0, s42, 0x1a000
	s_add_i32 s47, s42, 0x8000
	s_add_i32 s48, s42, 0xa000
	global_load_lds_dwordx4 v[2:3], off
	v_lshl_add_u64 v[2:3], v[6:7], 0, s[6:7]
	s_mov_b32 m0, s47
	s_add_u32 s12, s30, 0x80080
	global_load_lds_dwordx4 v[2:3], off
	v_lshl_add_u64 v[2:3], v[8:9], 0, s[6:7]
	s_mov_b32 m0, s48
	s_addc_u32 s13, s31, 0
	global_load_lds_dwordx4 v[2:3], off
	v_lshl_add_u64 v[2:3], s[12:13], 0, v[132:133]
	s_add_i32 m0, s42, 0x1c000
	v_lshl_add_u64 v[2:3], v[2:3], 0, v[130:131]
	global_load_lds_dwordx4 v[2:3], off
	v_lshl_add_u64 v[2:3], s[12:13], 0, v[136:137]
	v_lshl_add_u64 v[2:3], v[2:3], 0, v[130:131]
	s_add_i32 m0, s42, 0x1e000
	v_lshlrev_b32_e32 v4, 2, v0
	global_load_lds_dwordx4 v[2:3], off
	v_add_u32_e32 v132, v132, v130
	v_add_u32_e32 v136, v136, v130
	v_add_u32_e32 v138, v138, v130
	v_add_u32_e32 v140, v140, v130
	v_and_b32_e32 v2, 15, v0
	v_lshlrev_b32_e32 v3, 1, v12
	v_lshl_or_b32 v150, s10, 6, v2
	v_lshl_or_b32 v2, v2, 6, v3
	v_and_b32_e32 v4, 32, v4
	s_sext_i32_i16 s23, s8
	v_bitop3_b32 v5, v2, s11, v4 bitop3:0xde
	v_lshlrev_b32_e32 v2, 6, v0
	s_movk_i32 s8, 0x3c0
	v_and_or_b32 v2, v2, s8, v3
	s_cmpk_lt_u32 s9, 0x100
	v_lshlrev_b32_e32 v3, 9, v0
	v_bitop3_b32 v151, s14, v2, v4 bitop3:0xf6
	s_cselect_b64 s[8:9], -1, 0
	s_add_u32 s10, s86, 0x30000
	v_and_b32_e32 v3, 0x30000, v3
	v_lshlrev_b32_e32 v4, 12, v11
	v_add_u32_e32 v6, v13, v14
	s_addc_u32 s11, s87, 0
	v_or3_b32 v134, v3, v4, v6
	v_lshlrev_b32_e32 v3, 5, v10
	s_mov_b64 s[14:15], 0x80080
	s_waitcnt vmcnt(6)
	s_add_u32 s12, s86, 0x2400000
	v_and_b32_e32 v3, 0x70000, v3
	v_or_b32_e32 v2, s16, v12
	s_addc_u32 s13, s87, 0
	v_lshl_add_u64 v[142:143], v[134:135], 0, s[14:15]
	v_or3_b32 v134, v3, v4, v6
	s_add_i32 s49, 0, 0x10000
	s_add_i32 s50, 0, 0x14000
	v_lshl_add_u64 v[144:145], v[134:135], 0, s[14:15]
	v_add_u32_e32 v152, s49, v151
	v_add_u32_e32 v153, s50, v151
	v_add_u32_e32 v154, 0, v5
	v_mov_b32_e32 v155, 0x358637bd
	s_mov_b32 s51, 0x800000
	s_movk_i32 s52, 0x2c00
	v_lshlrev_b32_e32 v134, 1, v2
	s_mov_b64 s[20:21], s[30:31]
	s_mov_b64 s[16:17], s[28:29]
	s_barrier
	s_branch .LBB0_996

; #define PG8_STAGE(bufoff, gbase, RR, ld) do { _Pragma("unroll") for (int _i = 0; _i < 2; ++_i) \
;         __builtin_amdgcn_global_load_lds((const unsigned*)((const char*)(gbase) + (RR)[_i] * (ld) + C2[_i]), (LAS unsigned*)(lds + (bufoff) + ldsw + _i * 8192), 16, 0, 0); } while (0)
; #define PG8_LDA(dst, b, h) do { _Pragma("unroll") for (int m = 0; m < 4; ++m) _Pragma("unroll") for (int k = 0; k < 2; ++k) dst[m][k] = *(const LAS bf16x8*)(lds + PG8_SA(b, h) + aoff + m * 2048 + k * 1024); } while (0)
; #define PG8_LDB(dst, b, h) do { _Pragma("unroll") for (int n = 0; n < 2; ++n) _Pragma("unroll") for (int k = 0; k < 2; ++k) dst[n][k] = *(const LAS bf16x8*)(lds + PG8_SB(b, h) + boff + n * 2048 + k * 1024); } while (0)
; #define PG8_WAIT_V(n) asm volatile("s_waitcnt vmcnt(" #n ")" ::: "memory")
; #define PG8_WAIT_L(n) asm volatile("s_waitcnt lgkmcnt(" #n ")" ::: "memory")
; #define PG8_BAR __builtin_amdgcn_s_barrier()
; #define PG8_SCHED __builtin_amdgcn_sched_barrier(0)
; template <class Sched, class Epi>
; __device__ __forceinline__ void gemm_run(LAS unsigned char* lds, const Sched& S, const Epi& E) {
;     ...
;         for (int t = 0; t < nt; t += 2) {
;             const bool last = (t == nt - 2);
;             const char* a1 = cA + (size_t)(t + 1) * kstep;
;             const char* a2 = last ? nA : cA + (size_t)(t + 2) * kstep; const char* b2 = last ? nB : cB + (size_t)(t + 2) * kstep;
;             const unsigned la2 = last ? nlda : lda, lb2 = last ? nldb : ldb;
;             const char* a3 = a2 + kstep; const char* b3 = b2 + kstep;
;             PG8_LDB(B0, 0, 0); PG8_LDB(B1, 0, 1); PG8_SCHED; PG8_LDA(At, 0, 0); PG8_STAGE(PG8_SA(1, 1), a1 + (size_t)HALF * lda, RA, lda);
;             PG8_WAIT_V(8); PG8_WAIT_L(0); PG8_BAR; PG8_MMA(0, 0, At, B0); PG8_MMA(0, 1, At, B1); PG8_BAR; PG8_SCHED;
;             PG8_LDA(At, 0, 1); PG8_STAGE(PG8_SB(0, 0), b2, RB, lb2); PG8_STAGE(PG8_SB(0, 1), b2 + (size_t)HALF * lb2, RB, lb2); PG8_STAGE(PG8_SA(0, 0), a2, RA, la2);
;             PG8_WAIT_V(8); PG8_WAIT_L(0); PG8_BAR; PG8_MMA(1, 0, At, B0); PG8_MMA(1, 1, At, B1); PG8_BAR; PG8_SCHED;
;             PG8_LDB(B0, 1, 0); PG8_LDB(B1, 1, 1); PG8_SCHED; PG8_LDA(At, 1, 0); PG8_STAGE(PG8_SA(0, 1), a2 + (size_t)HALF * la2, RA, la2);
;             PG8_WAIT_V(8); PG8_WAIT_L(0); PG8_BAR; PG8_MMA(0, 0, At, B0); PG8_MMA(0, 1, At, B1); PG8_BAR; PG8_SCHED;
.LBB0_998:
	s_add_u32 s15, s30, 0x100
	s_addc_u32 s54, s31, 0
	s_mov_b32 s55, -2
	s_mov_b64 s[30:31], 0
	ds_read_b128 v[156:159], v152
	ds_read_b128 v[160:163], v152 offset:1024
	ds_read_b128 v[164:167], v152 offset:2048
	ds_read_b128 v[168:171], v152 offset:3072
	ds_read_b128 v[172:175], v153
	ds_read_b128 v[176:179], v153 offset:1024
	ds_read_b128 v[180:183], v153 offset:2048
	ds_read_b128 v[184:187], v153 offset:3072
	s_add_u32 s36, s28, s30
	s_addc_u32 s37, s29, s31
	s_mov_b32 s98, s36
	s_mov_b32 s99, s37
	s_add_u32 s36, s36, 0x100
	s_addc_u32 s37, s37, 0
	s_add_u32 s56, s15, s30
	s_addc_u32 s57, s54, s31
	s_cmpk_eq_i32 s30, 0xf00
	s_cselect_b32 s39, s17, s37
	s_cselect_b32 s38, s16, s36
	s_cselect_b32 s37, s21, s57
	s_cselect_b32 s36, s20, s56
	s_mov_b64 s[100:101], s[38:39]
	s_add_i32 m0, s42, 0xc000
	ds_read_b128 v[188:191], v154
	ds_read_b128 v[192:195], v154 offset:1024
	ds_read_b128 v[196:199], v154 offset:2048
	ds_read_b128 v[200:203], v154 offset:3072
	ds_read_b128 v[204:207], v154 offset:4096
	ds_read_b128 v[208:211], v154 offset:5120
	ds_read_b128 v[212:215], v154 offset:6144
	ds_read_b128 v[216:219], v154 offset:7168
	global_load_lds_dwordx4 v142, s[98:99]
	s_add_i32 m0, s42, 0xe000
	s_nop 0
	global_load_lds_dwordx4 v144, s[98:99]
	s_waitcnt vmcnt(8)
	s_waitcnt lgkmcnt(0)
	s_barrier
	s_waitcnt lgkmcnt(0)
	v_mfma_f32_16x16x32_bf16 v[126:129], v[156:159], v[188:191], 0
	v_mfma_f32_16x16x32_bf16 v[122:125], v[164:167], v[188:191], 0
	v_mfma_f32_16x16x32_bf16 v[110:113], v[156:159], v[196:199], 0
	v_mfma_f32_16x16x32_bf16 v[106:109], v[164:167], v[196:199], 0
	v_mfma_f32_16x16x32_bf16 v[94:97], v[156:159], v[204:207], 0
	v_mfma_f32_16x16x32_bf16 v[90:93], v[164:167], v[204:207], 0
	v_mfma_f32_16x16x32_bf16 v[78:81], v[156:159], v[212:215], 0
	v_mfma_f32_16x16x32_bf16 v[74:77], v[164:167], v[212:215], 0
	v_mfma_f32_16x16x32_bf16 v[126:129], v[160:163], v[192:195], v[126:129]
	v_mfma_f32_16x16x32_bf16 v[122:125], v[168:171], v[192:195], v[122:125]
	v_mfma_f32_16x16x32_bf16 v[110:113], v[160:163], v[200:203], v[110:113]
	v_mfma_f32_16x16x32_bf16 v[106:109], v[168:171], v[200:203], v[106:109]
	v_mfma_f32_16x16x32_bf16 v[94:97], v[160:163], v[208:211], v[94:97]
	v_mfma_f32_16x16x32_bf16 v[90:93], v[168:171], v[208:211], v[90:93]
	v_mfma_f32_16x16x32_bf16 v[78:81], v[160:163], v[216:219], v[78:81]
	v_mfma_f32_16x16x32_bf16 v[74:77], v[168:171], v[216:219], v[74:77]
	v_mfma_f32_16x16x32_bf16 v[118:121], v[172:175], v[188:191], 0
	v_mfma_f32_16x16x32_bf16 v[114:117], v[180:183], v[188:191], 0
	v_mfma_f32_16x16x32_bf16 v[102:105], v[172:175], v[196:199], 0
	v_mfma_f32_16x16x32_bf16 v[98:101], v[180:183], v[196:199], 0
	v_mfma_f32_16x16x32_bf16 v[86:89], v[172:175], v[204:207], 0
	v_mfma_f32_16x16x32_bf16 v[82:85], v[180:183], v[204:207], 0
	v_mfma_f32_16x16x32_bf16 v[70:73], v[172:175], v[212:215], 0
	v_mfma_f32_16x16x32_bf16 v[66:69], v[180:183], v[212:215], 0
	v_mfma_f32_16x16x32_bf16 v[118:121], v[176:179], v[192:195], v[118:121]
	v_mfma_f32_16x16x32_bf16 v[114:117], v[184:187], v[192:195], v[114:117]
	v_mfma_f32_16x16x32_bf16 v[102:105], v[176:179], v[200:203], v[102:105]
	v_mfma_f32_16x16x32_bf16 v[98:101], v[184:187], v[200:203], v[98:101]
	v_mfma_f32_16x16x32_bf16 v[86:89], v[176:179], v[208:211], v[86:89]
	v_mfma_f32_16x16x32_bf16 v[82:85], v[184:187], v[208:211], v[82:85]
	v_mfma_f32_16x16x32_bf16 v[70:73], v[176:179], v[216:219], v[70:73]
	v_mfma_f32_16x16x32_bf16 v[66:69], v[184:187], v[216:219], v[66:69]
	s_barrier
	s_add_i32 s56, s49, s3
	s_mov_b32 m0, s56
	ds_read_b128 v[188:191], v154 offset:16384
	ds_read_b128 v[192:195], v154 offset:17408
	ds_read_b128 v[196:199], v154 offset:18432
	ds_read_b128 v[200:203], v154 offset:19456
	ds_read_b128 v[204:207], v154 offset:20480
	ds_read_b128 v[208:211], v154 offset:21504
	ds_read_b128 v[212:215], v154 offset:22528
	ds_read_b128 v[216:219], v154 offset:23552
	global_load_lds_dwordx4 v132, s[36:37]
	s_add_i32 m0, s56, 0x2000
	s_add_u32 s56, s36, 0x80000
	s_addc_u32 s57, s37, 0
	s_add_i32 s58, s50, s3
	global_load_lds_dwordx4 v136, s[36:37]
	s_mov_b32 m0, s58
	s_nop 0
	global_load_lds_dwordx4 v132, s[56:57]
	s_add_i32 m0, s58, 0x2000
	s_nop 0
	global_load_lds_dwordx4 v136, s[56:57]
	s_mov_b32 m0, s42
	s_nop 0
	global_load_lds_dwordx4 v138, s[38:39]
	s_mov_b32 m0, s43
	s_nop 0
	global_load_lds_dwordx4 v140, s[38:39]
	s_waitcnt vmcnt(8)
	s_waitcnt lgkmcnt(0)
	s_barrier
	s_waitcnt lgkmcnt(0)
	v_mfma_f32_16x16x32_bf16 v[62:65], v[156:159], v[188:191], 0
	v_mfma_f32_16x16x32_bf16 v[58:61], v[164:167], v[188:191], 0
	v_mfma_f32_16x16x32_bf16 v[46:49], v[156:159], v[196:199], 0
	v_mfma_f32_16x16x32_bf16 v[42:45], v[164:167], v[196:199], 0
	v_mfma_f32_16x16x32_bf16 v[30:33], v[156:159], v[204:207], 0
	v_mfma_f32_16x16x32_bf16 v[26:29], v[164:167], v[204:207], 0
	v_mfma_f32_16x16x32_bf16 v[14:17], v[156:159], v[212:215], 0
	v_mfma_f32_16x16x32_bf16 v[10:13], v[164:167], v[212:215], 0
	v_mfma_f32_16x16x32_bf16 v[62:65], v[160:163], v[192:195], v[62:65]
	v_mfma_f32_16x16x32_bf16 v[58:61], v[168:171], v[192:195], v[58:61]
	v_mfma_f32_16x16x32_bf16 v[46:49], v[160:163], v[200:203], v[46:49]
	v_mfma_f32_16x16x32_bf16 v[42:45], v[168:171], v[200:203], v[42:45]
	v_mfma_f32_16x16x32_bf16 v[30:33], v[160:163], v[208:211], v[30:33]
	v_mfma_f32_16x16x32_bf16 v[26:29], v[168:171], v[208:211], v[26:29]
	v_mfma_f32_16x16x32_bf16 v[14:17], v[160:163], v[216:219], v[14:17]
	v_mfma_f32_16x16x32_bf16 v[10:13], v[168:171], v[216:219], v[10:13]
	v_mfma_f32_16x16x32_bf16 v[54:57], v[172:175], v[188:191], 0
	v_mfma_f32_16x16x32_bf16 v[50:53], v[180:183], v[188:191], 0
	v_mfma_f32_16x16x32_bf16 v[38:41], v[172:175], v[196:199], 0
	v_mfma_f32_16x16x32_bf16 v[34:37], v[180:183], v[196:199], 0
	v_mfma_f32_16x16x32_bf16 v[22:25], v[172:175], v[204:207], 0
	v_mfma_f32_16x16x32_bf16 v[18:21], v[180:183], v[204:207], 0
	v_mfma_f32_16x16x32_bf16 v[6:9], v[172:175], v[212:215], 0
	v_mfma_f32_16x16x32_bf16 v[2:5], v[180:183], v[212:215], 0
	v_mfma_f32_16x16x32_bf16 v[54:57], v[176:179], v[192:195], v[54:57]
	v_mfma_f32_16x16x32_bf16 v[50:53], v[184:187], v[192:195], v[50:53]
	v_mfma_f32_16x16x32_bf16 v[38:41], v[176:179], v[200:203], v[38:41]
	v_mfma_f32_16x16x32_bf16 v[34:37], v[184:187], v[200:203], v[34:37]
	v_mfma_f32_16x16x32_bf16 v[22:25], v[176:179], v[208:211], v[22:25]
	v_mfma_f32_16x16x32_bf16 v[18:21], v[184:187], v[208:211], v[18:21]
	v_mfma_f32_16x16x32_bf16 v[6:9], v[176:179], v[216:219], v[6:9]
	v_mfma_f32_16x16x32_bf16 v[2:5], v[184:187], v[216:219], v[2:5]
	s_barrier
; #define PG8_STAGE(bufoff, gbase, RR, ld) do { _Pragma("unroll") for (int _i = 0; _i < 2; ++_i) \
;         __builtin_amdgcn_global_load_lds((const unsigned*)((const char*)(gbase) + (RR)[_i] * (ld) + C2[_i]), (LAS unsigned*)(lds + (bufoff) + ldsw + _i * 8192), 16, 0, 0); } while (0)
; #define PG8_LDA(dst, b, h) do { _Pragma("unroll") for (int m = 0; m < 4; ++m) _Pragma("unroll") for (int k = 0; k < 2; ++k) dst[m][k] = *(const LAS bf16x8*)(lds + PG8_SA(b, h) + aoff + m * 2048 + k * 1024); } while (0)
; #define PG8_LDB(dst, b, h) do { _Pragma("unroll") for (int n = 0; n < 2; ++n) _Pragma("unroll") for (int k = 0; k < 2; ++k) dst[n][k] = *(const LAS bf16x8*)(lds + PG8_SB(b, h) + boff + n * 2048 + k * 1024); } while (0)
; #define PG8_MMA(ai, bj, At, Bt) do { __builtin_amdgcn_s_setprio(1); _Pragma("unroll") for (int m = 0; m < 4; ++m) _Pragma("unroll") for (int n = 0; n < 2; ++n) _Pragma("unroll") for (int k = 0; k < 2; ++k) \
;         acc[ai][bj][m][n] = __builtin_amdgcn_mfma_f32_16x16x32_bf16(Bt[n][k], At[m][k], acc[ai][bj][m][n], 0, 0, 0); __builtin_amdgcn_s_setprio(0); } while (0)
; #define PG8_WAIT_V(n) asm volatile("s_waitcnt vmcnt(" #n ")" ::: "memory")
; #define PG8_WAIT_L(n) asm volatile("s_waitcnt lgkmcnt(" #n ")" ::: "memory")
; #define PG8_BAR __builtin_amdgcn_s_barrier()
; #define PG8_SCHED __builtin_amdgcn_sched_barrier(0)
; template <class Sched, class Epi>
; __device__ __forceinline__ void gemm_run(LAS unsigned char* lds, const Sched& S, const Epi& E) {
;     ...
;             PG8_LDB(B0, 1, 0); PG8_LDB(B1, 1, 1); PG8_SCHED; PG8_LDA(At, 1, 0); PG8_STAGE(PG8_SA(0, 1), a2 + (size_t)HALF * la2, RA, la2);
;             PG8_WAIT_V(8); PG8_WAIT_L(0); PG8_BAR; PG8_MMA(0, 0, At, B0); PG8_MMA(0, 1, At, B1); PG8_BAR; PG8_SCHED;
;             PG8_LDA(At, 1, 1); PG8_STAGE(PG8_SB(1, 0), b3, RB, lb2); PG8_STAGE(PG8_SB(1, 1), b3 + (size_t)HALF * lb2, RB, lb2); PG8_STAGE(PG8_SA(1, 0), a3, RA, la2);
;             PG8_WAIT_V(8); PG8_WAIT_L(0); PG8_BAR; PG8_MMA(1, 0, At, B0); PG8_MMA(1, 1, At, B1); PG8_BAR; PG8_SCHED;
;         }
	s_add_i32 s56, 0, 0x18000
	s_add_i32 s57, 0, 0x1c000
	v_add_u32_e32 v168, s56, v151
	v_add_u32_e32 v184, s57, v151
	ds_read_b128 v[156:159], v168
	ds_read_b128 v[160:163], v168 offset:1024
	ds_read_b128 v[164:167], v168 offset:2048
	ds_read_b128 v[168:171], v168 offset:3072
	ds_read_b128 v[172:175], v184
	ds_read_b128 v[176:179], v184 offset:1024
	ds_read_b128 v[180:183], v184 offset:2048
	ds_read_b128 v[184:187], v184 offset:3072
	s_add_u32 s38, s38, 0x80000
	s_addc_u32 s39, s39, 0
	s_mov_b32 m0, s44
	ds_read_b128 v[188:191], v154 offset:32768
	ds_read_b128 v[192:195], v154 offset:33792
	ds_read_b128 v[196:199], v154 offset:34816
	ds_read_b128 v[200:203], v154 offset:35840
	ds_read_b128 v[204:207], v154 offset:36864
	ds_read_b128 v[208:211], v154 offset:37888
	ds_read_b128 v[212:215], v154 offset:38912
	ds_read_b128 v[216:219], v154 offset:39936
	global_load_lds_dwordx4 v138, s[38:39]
	s_mov_b32 m0, s45
	s_nop 0
	global_load_lds_dwordx4 v140, s[38:39]
	s_waitcnt vmcnt(8)
	s_waitcnt lgkmcnt(0)
	s_barrier
	s_waitcnt lgkmcnt(0)
	v_mfma_f32_16x16x32_bf16 v[126:129], v[156:159], v[188:191], v[126:129]
	v_mfma_f32_16x16x32_bf16 v[122:125], v[164:167], v[188:191], v[122:125]
	v_mfma_f32_16x16x32_bf16 v[110:113], v[156:159], v[196:199], v[110:113]
	v_mfma_f32_16x16x32_bf16 v[106:109], v[164:167], v[196:199], v[106:109]
	v_mfma_f32_16x16x32_bf16 v[94:97], v[156:159], v[204:207], v[94:97]
	v_mfma_f32_16x16x32_bf16 v[90:93], v[164:167], v[204:207], v[90:93]
	v_mfma_f32_16x16x32_bf16 v[78:81], v[156:159], v[212:215], v[78:81]
	v_mfma_f32_16x16x32_bf16 v[74:77], v[164:167], v[212:215], v[74:77]
	v_mfma_f32_16x16x32_bf16 v[126:129], v[160:163], v[192:195], v[126:129]
	v_mfma_f32_16x16x32_bf16 v[122:125], v[168:171], v[192:195], v[122:125]
	v_mfma_f32_16x16x32_bf16 v[110:113], v[160:163], v[200:203], v[110:113]
	v_mfma_f32_16x16x32_bf16 v[106:109], v[168:171], v[200:203], v[106:109]
	v_mfma_f32_16x16x32_bf16 v[94:97], v[160:163], v[208:211], v[94:97]
	v_mfma_f32_16x16x32_bf16 v[90:93], v[168:171], v[208:211], v[90:93]
	v_mfma_f32_16x16x32_bf16 v[78:81], v[160:163], v[216:219], v[78:81]
	v_mfma_f32_16x16x32_bf16 v[74:77], v[168:171], v[216:219], v[74:77]
	v_mfma_f32_16x16x32_bf16 v[118:121], v[172:175], v[188:191], v[118:121]
	v_mfma_f32_16x16x32_bf16 v[114:117], v[180:183], v[188:191], v[114:117]
	v_mfma_f32_16x16x32_bf16 v[102:105], v[172:175], v[196:199], v[102:105]
	v_mfma_f32_16x16x32_bf16 v[98:101], v[180:183], v[196:199], v[98:101]
	v_mfma_f32_16x16x32_bf16 v[86:89], v[172:175], v[204:207], v[86:89]
	v_mfma_f32_16x16x32_bf16 v[82:85], v[180:183], v[204:207], v[82:85]
	v_mfma_f32_16x16x32_bf16 v[70:73], v[172:175], v[212:215], v[70:73]
	v_mfma_f32_16x16x32_bf16 v[66:69], v[180:183], v[212:215], v[66:69]
	v_mfma_f32_16x16x32_bf16 v[118:121], v[176:179], v[192:195], v[118:121]
	v_mfma_f32_16x16x32_bf16 v[114:117], v[184:187], v[192:195], v[114:117]
	v_mfma_f32_16x16x32_bf16 v[102:105], v[176:179], v[200:203], v[102:105]
	v_mfma_f32_16x16x32_bf16 v[98:101], v[184:187], v[200:203], v[98:101]
	v_mfma_f32_16x16x32_bf16 v[86:89], v[176:179], v[208:211], v[86:89]
	v_mfma_f32_16x16x32_bf16 v[82:85], v[184:187], v[208:211], v[82:85]
	v_mfma_f32_16x16x32_bf16 v[70:73], v[176:179], v[216:219], v[70:73]
	v_mfma_f32_16x16x32_bf16 v[66:69], v[184:187], v[216:219], v[66:69]
	s_barrier
	s_add_i32 s38, s56, s3
	s_mov_b32 m0, s38
	ds_read_b128 v[188:191], v154 offset:49152
	ds_read_b128 v[192:195], v154 offset:50176
	ds_read_b128 v[196:199], v154 offset:51200
	ds_read_b128 v[200:203], v154 offset:52224
	ds_read_b128 v[204:207], v154 offset:53248
	ds_read_b128 v[208:211], v154 offset:54272
	ds_read_b128 v[212:215], v154 offset:55296
	ds_read_b128 v[216:219], v154 offset:56320
	s_add_u32 s98, s36, 0x80
	s_addc_u32 s99, s37, 0
	global_load_lds_dwordx4 v132, s[98:99]
	s_add_i32 m0, s38, 0x2000
	s_nop 0
	global_load_lds_dwordx4 v136, s[98:99]
	s_add_u32 s36, s36, 0x80080
	s_addc_u32 s37, s37, 0
	s_add_i32 s38, s57, s3
	s_mov_b32 m0, s38
	s_nop 0
	global_load_lds_dwordx4 v132, s[36:37]
	s_add_i32 m0, s38, 0x2000
	s_nop 0
	global_load_lds_dwordx4 v136, s[36:37]
	s_mov_b32 m0, s47
	s_nop 0
	s_add_u32 s100, s100, 0x80
	s_addc_u32 s101, s101, 0
	global_load_lds_dwordx4 v138, s[100:101]
	s_mov_b32 m0, s48
	s_nop 0
	global_load_lds_dwordx4 v140, s[100:101]
	s_waitcnt vmcnt(8)
	s_waitcnt lgkmcnt(0)
	s_barrier
	s_waitcnt lgkmcnt(0)
	v_mfma_f32_16x16x32_bf16 v[62:65], v[156:159], v[188:191], v[62:65]
	v_mfma_f32_16x16x32_bf16 v[58:61], v[164:167], v[188:191], v[58:61]
	v_mfma_f32_16x16x32_bf16 v[46:49], v[156:159], v[196:199], v[46:49]
	v_mfma_f32_16x16x32_bf16 v[42:45], v[164:167], v[196:199], v[42:45]
	v_mfma_f32_16x16x32_bf16 v[30:33], v[156:159], v[204:207], v[30:33]
	v_mfma_f32_16x16x32_bf16 v[26:29], v[164:167], v[204:207], v[26:29]
	v_mfma_f32_16x16x32_bf16 v[14:17], v[156:159], v[212:215], v[14:17]
	v_mfma_f32_16x16x32_bf16 v[10:13], v[164:167], v[212:215], v[10:13]
	v_mfma_f32_16x16x32_bf16 v[62:65], v[160:163], v[192:195], v[62:65]
	v_mfma_f32_16x16x32_bf16 v[58:61], v[168:171], v[192:195], v[58:61]
	v_mfma_f32_16x16x32_bf16 v[46:49], v[160:163], v[200:203], v[46:49]
	v_mfma_f32_16x16x32_bf16 v[42:45], v[168:171], v[200:203], v[42:45]
	v_mfma_f32_16x16x32_bf16 v[30:33], v[160:163], v[208:211], v[30:33]
	v_mfma_f32_16x16x32_bf16 v[26:29], v[168:171], v[208:211], v[26:29]
	v_mfma_f32_16x16x32_bf16 v[14:17], v[160:163], v[216:219], v[14:17]
	v_mfma_f32_16x16x32_bf16 v[10:13], v[168:171], v[216:219], v[10:13]
	v_mfma_f32_16x16x32_bf16 v[54:57], v[172:175], v[188:191], v[54:57]
	v_mfma_f32_16x16x32_bf16 v[50:53], v[180:183], v[188:191], v[50:53]
	v_mfma_f32_16x16x32_bf16 v[38:41], v[172:175], v[196:199], v[38:41]
	v_mfma_f32_16x16x32_bf16 v[34:37], v[180:183], v[196:199], v[34:37]
	v_mfma_f32_16x16x32_bf16 v[22:25], v[172:175], v[204:207], v[22:25]
	v_mfma_f32_16x16x32_bf16 v[18:21], v[180:183], v[204:207], v[18:21]
	v_mfma_f32_16x16x32_bf16 v[6:9], v[172:175], v[212:215], v[6:9]
	v_mfma_f32_16x16x32_bf16 v[2:5], v[180:183], v[212:215], v[2:5]
	v_mfma_f32_16x16x32_bf16 v[54:57], v[176:179], v[192:195], v[54:57]
	v_mfma_f32_16x16x32_bf16 v[50:53], v[184:187], v[192:195], v[50:53]
	v_mfma_f32_16x16x32_bf16 v[38:41], v[176:179], v[200:203], v[38:41]
	v_mfma_f32_16x16x32_bf16 v[34:37], v[184:187], v[200:203], v[34:37]
	v_mfma_f32_16x16x32_bf16 v[22:25], v[176:179], v[208:211], v[22:25]
	v_mfma_f32_16x16x32_bf16 v[18:21], v[184:187], v[208:211], v[18:21]
	v_mfma_f32_16x16x32_bf16 v[6:9], v[176:179], v[216:219], v[6:9]
	v_mfma_f32_16x16x32_bf16 v[2:5], v[184:187], v[216:219], v[2:5]
	s_barrier
	s_add_i32 s55, s55, 2
	s_add_u32 s30, s30, 0x100
	s_addc_u32 s31, s31, 0
	s_cmp_gt_u32 s55, 29
	s_cbranch_scc0 .LBB0_999
	.p2align 6
; #define PG8_STAGE(bufoff, gbase, RR, ld) do { _Pragma("unroll") for (int _i = 0; _i < 2; ++_i) \
;         __builtin_amdgcn_global_load_lds((const unsigned*)((const char*)(gbase) + (RR)[_i] * (ld) + C2[_i]), (LAS unsigned*)(lds + (bufoff) + ldsw + _i * 8192), 16, 0, 0); } while (0)
; #define PG8_LDA(dst, b, h) do { _Pragma("unroll") for (int m = 0; m < 4; ++m) _Pragma("unroll") for (int k = 0; k < 2; ++k) dst[m][k] = *(const LAS bf16x8*)(lds + PG8_SA(b, h) + aoff + m * 2048 + k * 1024); } while (0)
; #define PG8_LDB(dst, b, h) do { _Pragma("unroll") for (int n = 0; n < 2; ++n) _Pragma("unroll") for (int k = 0; k < 2; ++k) dst[n][k] = *(const LAS bf16x8*)(lds + PG8_SB(b, h) + boff + n * 2048 + k * 1024); } while (0)
; #define PG8_MMA(ai, bj, At, Bt) do { __builtin_amdgcn_s_setprio(1); _Pragma("unroll") for (int m = 0; m < 4; ++m) _Pragma("unroll") for (int n = 0; n < 2; ++n) _Pragma("unroll") for (int k = 0; k < 2; ++k) \
;         acc[ai][bj][m][n] = __builtin_amdgcn_mfma_f32_16x16x32_bf16(Bt[n][k], At[m][k], acc[ai][bj][m][n], 0, 0, 0); __builtin_amdgcn_s_setprio(0); } while (0)
; #define PG8_WAIT_V(n) asm volatile("s_waitcnt vmcnt(" #n ")" ::: "memory")
; #define PG8_WAIT_L(n) asm volatile("s_waitcnt lgkmcnt(" #n ")" ::: "memory")
; template <class Sched, class Epi>
; __device__ __forceinline__ void gemm_run(LAS unsigned char* lds, const Sched& S, const Epi& E) {
;     ...
;         for (int t = 0; t < nt; t += 2) {
;             const bool last = (t == nt - 2);
;             const char* a1 = cA + (size_t)(t + 1) * kstep;
;             const char* a2 = last ? nA : cA + (size_t)(t + 2) * kstep; const char* b2 = last ? nB : cB + (size_t)(t + 2) * kstep;
;             const unsigned la2 = last ? nlda : lda, lb2 = last ? nldb : ldb;
;             const char* a3 = a2 + kstep; const char* b3 = b2 + kstep;
;             PG8_LDB(B0, 0, 0); PG8_LDB(B1, 0, 1); PG8_SCHED; PG8_LDA(At, 0, 0); PG8_STAGE(PG8_SA(1, 1), a1 + (size_t)HALF * lda, RA, lda);
;             PG8_WAIT_V(8); PG8_WAIT_L(0); PG8_BAR; PG8_MMA(0, 0, At, B0); PG8_MMA(0, 1, At, B1); PG8_BAR; PG8_SCHED;
;             PG8_LDA(At, 0, 1); PG8_STAGE(PG8_SB(0, 0), b2, RB, lb2); PG8_STAGE(PG8_SB(0, 1), b2 + (size_t)HALF * lb2, RB, lb2); PG8_STAGE(PG8_SA(0, 0), a2, RA, la2);
;             PG8_WAIT_V(8); PG8_WAIT_L(0); PG8_BAR; PG8_MMA(1, 0, At, B0); PG8_MMA(1, 1, At, B1); PG8_BAR; PG8_SCHED;
.LBB0_999:
	ds_read_b128 v[156:159], v152
	ds_read_b128 v[160:163], v152 offset:1024
	ds_read_b128 v[164:167], v152 offset:2048
	ds_read_b128 v[168:171], v152 offset:3072
	ds_read_b128 v[172:175], v153
	ds_read_b128 v[176:179], v153 offset:1024
	ds_read_b128 v[180:183], v153 offset:2048
	ds_read_b128 v[184:187], v153 offset:3072
	s_add_u32 s36, s28, s30
	s_addc_u32 s37, s29, s31
	s_mov_b32 s98, s36
	s_mov_b32 s99, s37
	s_add_u32 s36, s36, 0x100
	s_addc_u32 s37, s37, 0
	s_add_u32 s56, s15, s30
	s_addc_u32 s57, s54, s31
	s_cmpk_eq_i32 s30, 0xf00
	s_cselect_b32 s39, s17, s37
	s_cselect_b32 s38, s16, s36
	s_cselect_b32 s37, s21, s57
	s_cselect_b32 s36, s20, s56
	s_mov_b64 s[100:101], s[38:39]
	s_add_i32 m0, s42, 0xc000
	ds_read_b128 v[188:191], v154
	ds_read_b128 v[192:195], v154 offset:1024
	ds_read_b128 v[196:199], v154 offset:2048
	ds_read_b128 v[200:203], v154 offset:3072
	ds_read_b128 v[204:207], v154 offset:4096
	ds_read_b128 v[208:211], v154 offset:5120
	ds_read_b128 v[212:215], v154 offset:6144
	ds_read_b128 v[216:219], v154 offset:7168
	global_load_lds_dwordx4 v142, s[98:99]
	s_add_i32 m0, s42, 0xe000
	s_nop 0
	global_load_lds_dwordx4 v144, s[98:99]
	s_waitcnt vmcnt(8)
	s_waitcnt lgkmcnt(0)
	s_barrier
	s_waitcnt lgkmcnt(0)
	v_mfma_f32_16x16x32_bf16 v[126:129], v[156:159], v[188:191], v[126:129]
	v_mfma_f32_16x16x32_bf16 v[122:125], v[164:167], v[188:191], v[122:125]
	v_mfma_f32_16x16x32_bf16 v[110:113], v[156:159], v[196:199], v[110:113]
	v_mfma_f32_16x16x32_bf16 v[106:109], v[164:167], v[196:199], v[106:109]
	v_mfma_f32_16x16x32_bf16 v[94:97], v[156:159], v[204:207], v[94:97]
	v_mfma_f32_16x16x32_bf16 v[90:93], v[164:167], v[204:207], v[90:93]
	v_mfma_f32_16x16x32_bf16 v[78:81], v[156:159], v[212:215], v[78:81]
	v_mfma_f32_16x16x32_bf16 v[74:77], v[164:167], v[212:215], v[74:77]
	v_mfma_f32_16x16x32_bf16 v[126:129], v[160:163], v[192:195], v[126:129]
	v_mfma_f32_16x16x32_bf16 v[122:125], v[168:171], v[192:195], v[122:125]
	v_mfma_f32_16x16x32_bf16 v[110:113], v[160:163], v[200:203], v[110:113]
	v_mfma_f32_16x16x32_bf16 v[106:109], v[168:171], v[200:203], v[106:109]
	v_mfma_f32_16x16x32_bf16 v[94:97], v[160:163], v[208:211], v[94:97]
	v_mfma_f32_16x16x32_bf16 v[90:93], v[168:171], v[208:211], v[90:93]
	v_mfma_f32_16x16x32_bf16 v[78:81], v[160:163], v[216:219], v[78:81]
	v_mfma_f32_16x16x32_bf16 v[74:77], v[168:171], v[216:219], v[74:77]
	v_mfma_f32_16x16x32_bf16 v[118:121], v[172:175], v[188:191], v[118:121]
	v_mfma_f32_16x16x32_bf16 v[114:117], v[180:183], v[188:191], v[114:117]
	v_mfma_f32_16x16x32_bf16 v[102:105], v[172:175], v[196:199], v[102:105]
	v_mfma_f32_16x16x32_bf16 v[98:101], v[180:183], v[196:199], v[98:101]
	v_mfma_f32_16x16x32_bf16 v[86:89], v[172:175], v[204:207], v[86:89]
	v_mfma_f32_16x16x32_bf16 v[82:85], v[180:183], v[204:207], v[82:85]
	v_mfma_f32_16x16x32_bf16 v[70:73], v[172:175], v[212:215], v[70:73]
	v_mfma_f32_16x16x32_bf16 v[66:69], v[180:183], v[212:215], v[66:69]
	v_mfma_f32_16x16x32_bf16 v[118:121], v[176:179], v[192:195], v[118:121]
	v_mfma_f32_16x16x32_bf16 v[114:117], v[184:187], v[192:195], v[114:117]
	v_mfma_f32_16x16x32_bf16 v[102:105], v[176:179], v[200:203], v[102:105]
	v_mfma_f32_16x16x32_bf16 v[98:101], v[184:187], v[200:203], v[98:101]
	v_mfma_f32_16x16x32_bf16 v[86:89], v[176:179], v[208:211], v[86:89]
	v_mfma_f32_16x16x32_bf16 v[82:85], v[184:187], v[208:211], v[82:85]
	v_mfma_f32_16x16x32_bf16 v[70:73], v[176:179], v[216:219], v[70:73]
	v_mfma_f32_16x16x32_bf16 v[66:69], v[184:187], v[216:219], v[66:69]
	s_barrier
	s_add_i32 s56, s49, s3
	s_mov_b32 m0, s56
	ds_read_b128 v[188:191], v154 offset:16384
	ds_read_b128 v[192:195], v154 offset:17408
	ds_read_b128 v[196:199], v154 offset:18432
	ds_read_b128 v[200:203], v154 offset:19456
	ds_read_b128 v[204:207], v154 offset:20480
	ds_read_b128 v[208:211], v154 offset:21504
	ds_read_b128 v[212:215], v154 offset:22528
	ds_read_b128 v[216:219], v154 offset:23552
	global_load_lds_dwordx4 v132, s[36:37]
	s_add_i32 m0, s56, 0x2000
	s_add_u32 s56, s36, 0x80000
	s_addc_u32 s57, s37, 0
	s_add_i32 s58, s50, s3
	global_load_lds_dwordx4 v136, s[36:37]
	s_mov_b32 m0, s58
	s_nop 0
	global_load_lds_dwordx4 v132, s[56:57]
	s_add_i32 m0, s58, 0x2000
	s_nop 0
	global_load_lds_dwordx4 v136, s[56:57]
	s_mov_b32 m0, s42
	s_nop 0
	global_load_lds_dwordx4 v138, s[38:39]
	s_mov_b32 m0, s43
	s_nop 0
	global_load_lds_dwordx4 v140, s[38:39]
	s_waitcnt vmcnt(8)
	s_waitcnt lgkmcnt(0)
	s_barrier
	s_waitcnt lgkmcnt(0)
	v_mfma_f32_16x16x32_bf16 v[62:65], v[156:159], v[188:191], v[62:65]
	v_mfma_f32_16x16x32_bf16 v[58:61], v[164:167], v[188:191], v[58:61]
	v_mfma_f32_16x16x32_bf16 v[46:49], v[156:159], v[196:199], v[46:49]
	v_mfma_f32_16x16x32_bf16 v[42:45], v[164:167], v[196:199], v[42:45]
	v_mfma_f32_16x16x32_bf16 v[30:33], v[156:159], v[204:207], v[30:33]
	v_mfma_f32_16x16x32_bf16 v[26:29], v[164:167], v[204:207], v[26:29]
	v_mfma_f32_16x16x32_bf16 v[14:17], v[156:159], v[212:215], v[14:17]
	v_mfma_f32_16x16x32_bf16 v[10:13], v[164:167], v[212:215], v[10:13]
	v_mfma_f32_16x16x32_bf16 v[62:65], v[160:163], v[192:195], v[62:65]
	v_mfma_f32_16x16x32_bf16 v[58:61], v[168:171], v[192:195], v[58:61]
	v_mfma_f32_16x16x32_bf16 v[46:49], v[160:163], v[200:203], v[46:49]
	v_mfma_f32_16x16x32_bf16 v[42:45], v[168:171], v[200:203], v[42:45]
	v_mfma_f32_16x16x32_bf16 v[30:33], v[160:163], v[208:211], v[30:33]
	v_mfma_f32_16x16x32_bf16 v[26:29], v[168:171], v[208:211], v[26:29]
	v_mfma_f32_16x16x32_bf16 v[14:17], v[160:163], v[216:219], v[14:17]
	v_mfma_f32_16x16x32_bf16 v[10:13], v[168:171], v[216:219], v[10:13]
	v_mfma_f32_16x16x32_bf16 v[54:57], v[172:175], v[188:191], v[54:57]
	v_mfma_f32_16x16x32_bf16 v[50:53], v[180:183], v[188:191], v[50:53]
	v_mfma_f32_16x16x32_bf16 v[38:41], v[172:175], v[196:199], v[38:41]
	v_mfma_f32_16x16x32_bf16 v[34:37], v[180:183], v[196:199], v[34:37]
	v_mfma_f32_16x16x32_bf16 v[22:25], v[172:175], v[204:207], v[22:25]
	v_mfma_f32_16x16x32_bf16 v[18:21], v[180:183], v[204:207], v[18:21]
	v_mfma_f32_16x16x32_bf16 v[6:9], v[172:175], v[212:215], v[6:9]
	v_mfma_f32_16x16x32_bf16 v[2:5], v[180:183], v[212:215], v[2:5]
	v_mfma_f32_16x16x32_bf16 v[54:57], v[176:179], v[192:195], v[54:57]
	v_mfma_f32_16x16x32_bf16 v[50:53], v[184:187], v[192:195], v[50:53]
	v_mfma_f32_16x16x32_bf16 v[38:41], v[176:179], v[200:203], v[38:41]
	v_mfma_f32_16x16x32_bf16 v[34:37], v[184:187], v[200:203], v[34:37]
	v_mfma_f32_16x16x32_bf16 v[22:25], v[176:179], v[208:211], v[22:25]
	v_mfma_f32_16x16x32_bf16 v[18:21], v[184:187], v[208:211], v[18:21]
	v_mfma_f32_16x16x32_bf16 v[6:9], v[176:179], v[216:219], v[6:9]
	v_mfma_f32_16x16x32_bf16 v[2:5], v[184:187], v[216:219], v[2:5]
	s_barrier
; #define PG8_STAGE(bufoff, gbase, RR, ld) do { _Pragma("unroll") for (int _i = 0; _i < 2; ++_i) \
;         __builtin_amdgcn_global_load_lds((const unsigned*)((const char*)(gbase) + (RR)[_i] * (ld) + C2[_i]), (LAS unsigned*)(lds + (bufoff) + ldsw + _i * 8192), 16, 0, 0); } while (0)
; #define PG8_LDA(dst, b, h) do { _Pragma("unroll") for (int m = 0; m < 4; ++m) _Pragma("unroll") for (int k = 0; k < 2; ++k) dst[m][k] = *(const LAS bf16x8*)(lds + PG8_SA(b, h) + aoff + m * 2048 + k * 1024); } while (0)
; #define PG8_LDB(dst, b, h) do { _Pragma("unroll") for (int n = 0; n < 2; ++n) _Pragma("unroll") for (int k = 0; k < 2; ++k) dst[n][k] = *(const LAS bf16x8*)(lds + PG8_SB(b, h) + boff + n * 2048 + k * 1024); } while (0)
; #define PG8_MMA(ai, bj, At, Bt) do { __builtin_amdgcn_s_setprio(1); _Pragma("unroll") for (int m = 0; m < 4; ++m) _Pragma("unroll") for (int n = 0; n < 2; ++n) _Pragma("unroll") for (int k = 0; k < 2; ++k) \
;         acc[ai][bj][m][n] = __builtin_amdgcn_mfma_f32_16x16x32_bf16(Bt[n][k], At[m][k], acc[ai][bj][m][n], 0, 0, 0); __builtin_amdgcn_s_setprio(0); } while (0)
; #define PG8_WAIT_V(n) asm volatile("s_waitcnt vmcnt(" #n ")" ::: "memory")
; #define PG8_WAIT_L(n) asm volatile("s_waitcnt lgkmcnt(" #n ")" ::: "memory")
; #define PG8_BAR __builtin_amdgcn_s_barrier()
; #define PG8_SCHED __builtin_amdgcn_sched_barrier(0)
; template <class Sched, class Epi>
; __device__ __forceinline__ void gemm_run(LAS unsigned char* lds, const Sched& S, const Epi& E) {
;     ...
;             PG8_LDB(B0, 1, 0); PG8_LDB(B1, 1, 1); PG8_SCHED; PG8_LDA(At, 1, 0); PG8_STAGE(PG8_SA(0, 1), a2 + (size_t)HALF * la2, RA, la2);
;             PG8_WAIT_V(8); PG8_WAIT_L(0); PG8_BAR; PG8_MMA(0, 0, At, B0); PG8_MMA(0, 1, At, B1); PG8_BAR; PG8_SCHED;
;             PG8_LDA(At, 1, 1); PG8_STAGE(PG8_SB(1, 0), b3, RB, lb2); PG8_STAGE(PG8_SB(1, 1), b3 + (size_t)HALF * lb2, RB, lb2); PG8_STAGE(PG8_SA(1, 0), a3, RA, la2);
;             PG8_WAIT_V(8); PG8_WAIT_L(0); PG8_BAR; PG8_MMA(1, 0, At, B0); PG8_MMA(1, 1, At, B1); PG8_BAR; PG8_SCHED;
;         }
	s_add_i32 s56, 0, 0x18000
	s_add_i32 s57, 0, 0x1c000
	v_add_u32_e32 v168, s56, v151
	v_add_u32_e32 v184, s57, v151
	ds_read_b128 v[156:159], v168
	ds_read_b128 v[160:163], v168 offset:1024
	ds_read_b128 v[164:167], v168 offset:2048
	ds_read_b128 v[168:171], v168 offset:3072
	ds_read_b128 v[172:175], v184
	ds_read_b128 v[176:179], v184 offset:1024
	ds_read_b128 v[180:183], v184 offset:2048
	ds_read_b128 v[184:187], v184 offset:3072
	s_add_u32 s38, s38, 0x80000
	s_addc_u32 s39, s39, 0
	s_mov_b32 m0, s44
	ds_read_b128 v[188:191], v154 offset:32768
	ds_read_b128 v[192:195], v154 offset:33792
	ds_read_b128 v[196:199], v154 offset:34816
	ds_read_b128 v[200:203], v154 offset:35840
	ds_read_b128 v[204:207], v154 offset:36864
	ds_read_b128 v[208:211], v154 offset:37888
	ds_read_b128 v[212:215], v154 offset:38912
	ds_read_b128 v[216:219], v154 offset:39936
	global_load_lds_dwordx4 v138, s[38:39]
	s_mov_b32 m0, s45
	s_nop 0
	global_load_lds_dwordx4 v140, s[38:39]
	s_waitcnt vmcnt(8)
	s_waitcnt lgkmcnt(0)
	s_barrier
	s_waitcnt lgkmcnt(0)
	v_mfma_f32_16x16x32_bf16 v[126:129], v[156:159], v[188:191], v[126:129]
	v_mfma_f32_16x16x32_bf16 v[122:125], v[164:167], v[188:191], v[122:125]
	v_mfma_f32_16x16x32_bf16 v[110:113], v[156:159], v[196:199], v[110:113]
	v_mfma_f32_16x16x32_bf16 v[106:109], v[164:167], v[196:199], v[106:109]
	v_mfma_f32_16x16x32_bf16 v[94:97], v[156:159], v[204:207], v[94:97]
	v_mfma_f32_16x16x32_bf16 v[90:93], v[164:167], v[204:207], v[90:93]
	v_mfma_f32_16x16x32_bf16 v[78:81], v[156:159], v[212:215], v[78:81]
	v_mfma_f32_16x16x32_bf16 v[74:77], v[164:167], v[212:215], v[74:77]
	v_mfma_f32_16x16x32_bf16 v[126:129], v[160:163], v[192:195], v[126:129]
	v_mfma_f32_16x16x32_bf16 v[122:125], v[168:171], v[192:195], v[122:125]
	v_mfma_f32_16x16x32_bf16 v[110:113], v[160:163], v[200:203], v[110:113]
	v_mfma_f32_16x16x32_bf16 v[106:109], v[168:171], v[200:203], v[106:109]
	v_mfma_f32_16x16x32_bf16 v[94:97], v[160:163], v[208:211], v[94:97]
	v_mfma_f32_16x16x32_bf16 v[90:93], v[168:171], v[208:211], v[90:93]
	v_mfma_f32_16x16x32_bf16 v[78:81], v[160:163], v[216:219], v[78:81]
	v_mfma_f32_16x16x32_bf16 v[74:77], v[168:171], v[216:219], v[74:77]
	v_mfma_f32_16x16x32_bf16 v[118:121], v[172:175], v[188:191], v[118:121]
	v_mfma_f32_16x16x32_bf16 v[114:117], v[180:183], v[188:191], v[114:117]
	v_mfma_f32_16x16x32_bf16 v[102:105], v[172:175], v[196:199], v[102:105]
	v_mfma_f32_16x16x32_bf16 v[98:101], v[180:183], v[196:199], v[98:101]
	v_mfma_f32_16x16x32_bf16 v[86:89], v[172:175], v[204:207], v[86:89]
	v_mfma_f32_16x16x32_bf16 v[82:85], v[180:183], v[204:207], v[82:85]
	v_mfma_f32_16x16x32_bf16 v[70:73], v[172:175], v[212:215], v[70:73]
	v_mfma_f32_16x16x32_bf16 v[66:69], v[180:183], v[212:215], v[66:69]
	v_mfma_f32_16x16x32_bf16 v[118:121], v[176:179], v[192:195], v[118:121]
	v_mfma_f32_16x16x32_bf16 v[114:117], v[184:187], v[192:195], v[114:117]
	v_mfma_f32_16x16x32_bf16 v[102:105], v[176:179], v[200:203], v[102:105]
	v_mfma_f32_16x16x32_bf16 v[98:101], v[184:187], v[200:203], v[98:101]
	v_mfma_f32_16x16x32_bf16 v[86:89], v[176:179], v[208:211], v[86:89]
	v_mfma_f32_16x16x32_bf16 v[82:85], v[184:187], v[208:211], v[82:85]
	v_mfma_f32_16x16x32_bf16 v[70:73], v[176:179], v[216:219], v[70:73]
	v_mfma_f32_16x16x32_bf16 v[66:69], v[184:187], v[216:219], v[66:69]
	s_barrier
	s_add_i32 s38, s56, s3
	s_mov_b32 m0, s38
	ds_read_b128 v[188:191], v154 offset:49152
	ds_read_b128 v[192:195], v154 offset:50176
	ds_read_b128 v[196:199], v154 offset:51200
	ds_read_b128 v[200:203], v154 offset:52224
	ds_read_b128 v[204:207], v154 offset:53248
	ds_read_b128 v[208:211], v154 offset:54272
	ds_read_b128 v[212:215], v154 offset:55296
	ds_read_b128 v[216:219], v154 offset:56320
	s_add_u32 s98, s36, 0x80
	s_addc_u32 s99, s37, 0
	global_load_lds_dwordx4 v132, s[98:99]
	s_add_i32 m0, s38, 0x2000
	s_nop 0
	global_load_lds_dwordx4 v136, s[98:99]
	s_add_u32 s36, s36, 0x80080
	s_addc_u32 s37, s37, 0
	s_add_i32 s38, s57, s3
	s_mov_b32 m0, s38
	s_nop 0
	global_load_lds_dwordx4 v132, s[36:37]
	s_add_i32 m0, s38, 0x2000
	s_nop 0
	global_load_lds_dwordx4 v136, s[36:37]
	s_mov_b32 m0, s47
	s_nop 0
	s_add_u32 s100, s100, 0x80
	s_addc_u32 s101, s101, 0
	global_load_lds_dwordx4 v138, s[100:101]
	s_mov_b32 m0, s48
	s_nop 0
	global_load_lds_dwordx4 v140, s[100:101]
	s_waitcnt vmcnt(8)
	s_waitcnt lgkmcnt(0)
	s_barrier
	s_waitcnt lgkmcnt(0)
	v_mfma_f32_16x16x32_bf16 v[62:65], v[156:159], v[188:191], v[62:65]
	v_mfma_f32_16x16x32_bf16 v[58:61], v[164:167], v[188:191], v[58:61]
	v_mfma_f32_16x16x32_bf16 v[46:49], v[156:159], v[196:199], v[46:49]
	v_mfma_f32_16x16x32_bf16 v[42:45], v[164:167], v[196:199], v[42:45]
	v_mfma_f32_16x16x32_bf16 v[30:33], v[156:159], v[204:207], v[30:33]
	v_mfma_f32_16x16x32_bf16 v[26:29], v[164:167], v[204:207], v[26:29]
	v_mfma_f32_16x16x32_bf16 v[14:17], v[156:159], v[212:215], v[14:17]
	v_mfma_f32_16x16x32_bf16 v[10:13], v[164:167], v[212:215], v[10:13]
	v_mfma_f32_16x16x32_bf16 v[62:65], v[160:163], v[192:195], v[62:65]
	v_mfma_f32_16x16x32_bf16 v[58:61], v[168:171], v[192:195], v[58:61]
	v_mfma_f32_16x16x32_bf16 v[46:49], v[160:163], v[200:203], v[46:49]
	v_mfma_f32_16x16x32_bf16 v[42:45], v[168:171], v[200:203], v[42:45]
	v_mfma_f32_16x16x32_bf16 v[30:33], v[160:163], v[208:211], v[30:33]
	v_mfma_f32_16x16x32_bf16 v[26:29], v[168:171], v[208:211], v[26:29]
	v_mfma_f32_16x16x32_bf16 v[14:17], v[160:163], v[216:219], v[14:17]
	v_mfma_f32_16x16x32_bf16 v[10:13], v[168:171], v[216:219], v[10:13]
	v_mfma_f32_16x16x32_bf16 v[54:57], v[172:175], v[188:191], v[54:57]
	v_mfma_f32_16x16x32_bf16 v[50:53], v[180:183], v[188:191], v[50:53]
	v_mfma_f32_16x16x32_bf16 v[38:41], v[172:175], v[196:199], v[38:41]
	v_mfma_f32_16x16x32_bf16 v[34:37], v[180:183], v[196:199], v[34:37]
	v_mfma_f32_16x16x32_bf16 v[22:25], v[172:175], v[204:207], v[22:25]
	v_mfma_f32_16x16x32_bf16 v[18:21], v[180:183], v[204:207], v[18:21]
	v_mfma_f32_16x16x32_bf16 v[6:9], v[172:175], v[212:215], v[6:9]
	v_mfma_f32_16x16x32_bf16 v[2:5], v[180:183], v[212:215], v[2:5]
	v_mfma_f32_16x16x32_bf16 v[54:57], v[176:179], v[192:195], v[54:57]
	v_mfma_f32_16x16x32_bf16 v[50:53], v[184:187], v[192:195], v[50:53]
	v_mfma_f32_16x16x32_bf16 v[38:41], v[176:179], v[200:203], v[38:41]
	v_mfma_f32_16x16x32_bf16 v[34:37], v[184:187], v[200:203], v[34:37]
	v_mfma_f32_16x16x32_bf16 v[22:25], v[176:179], v[208:211], v[22:25]
	v_mfma_f32_16x16x32_bf16 v[18:21], v[184:187], v[208:211], v[18:21]
	v_mfma_f32_16x16x32_bf16 v[6:9], v[176:179], v[216:219], v[6:9]
	v_mfma_f32_16x16x32_bf16 v[2:5], v[184:187], v[216:219], v[2:5]
	s_barrier
	s_add_i32 s55, s55, 2
	s_add_u32 s30, s30, 0x100
	s_addc_u32 s31, s31, 0
	s_cmp_gt_u32 s55, 29
	s_cbranch_scc0 .LBB0_999
	s_and_b64 vcc, exec, s[8:9]
	s_cbranch_vccz .LBB0_1002
	s_barrier
